# epilogue de-serialisation: in-projection plain (non-gate) tiles skip the four bias loads and the full vmcnt drain at the epilogue head; otherwise v19
# speedup vs baseline: 1.0141x; 1.0054x over previous
;     template <bool GATE> __device__ __forceinline__ void run(const f32x4 (&acc)[2][2][4][2], const Unit& u, int wr, int wc, int fr, int fq) const {
;         const int row0 = u.pm * BM + wr * 64 + fr, col0 = u.pn * BM + wc * 32 + 8 * fq;
;         const bool gate = (MODE == EP_INPROJ) && (u.pn >= gate_tile0);
;         f32x4 bv[2][2];
; #pragma unroll
;         for (int bj = 0; bj < 2; ++bj)
; #pragma unroll
;             for (int n = 0; n < 2; ++n) { bv[bj][n] = (f32x4){0.f, 0.f, 0.f, 0.f}; if (MODE == EP_INPROJ) bv[bj][n] = *(const f32x4*)(bias + (gate ? col0 - gate_tile0 * BM : 0) + bj * HALF + 4 * n); }
;         if (MODE == EP_INPROJ) asm volatile("" : "+v"(bv[0][0]), "+v"(bv[0][1]), "+v"(bv[1][0]), "+v"(bv[1][1]));
;     ...
;                     if (MODE == EP_INPROJ) { if (gate) { v0 = sigmoid4(v0 + bv[bj][0]); v1 = sigmoid4(v1 + bv[bj][1]); } }
.LBB0_159:
	v_lshl_or_b32 v156, s22, 8, v162
	s_cmp_gt_i32 s22, 23
	v_add_u32_e32 v60, 0xffffe800, v156
	s_cselect_b64 s[46:47], -1, 0
	v_cndmask_b32_e64 v60, 0, v60, s[46:47]
	v_ashrrev_i32_e32 v61, 31, v60
	v_lshl_add_u64 v[68:69], v[60:61], 2, s[48:49]
	s_cbranch_scc0 .Lp1_nobias
	global_load_dwordx4 v[72:75], v[68:69], off offset:16
	global_load_dwordx4 v[76:79], v[68:69], off
	global_load_dwordx4 v[60:63], v[68:69], off offset:528
	s_nop 0
	global_load_dwordx4 v[68:71], v[68:69], off offset:512
.Lp1_nobias:
	v_mov_b32_e32 v155, v140
	v_mov_b32_e32 v157, v141
	v_mov_b32_e32 v158, v142
	v_mov_b32_e32 v159, v143
	v_mov_b32_e32 v164, v136
	v_mov_b32_e32 v165, v137
	v_mov_b32_e32 v166, v138
	v_mov_b32_e32 v167, v139
	s_and_b64 vcc, exec, s[46:47]
	s_cbranch_vccz .LBB0_161
	s_waitcnt vmcnt(0)
	v_pk_add_f32 v[154:155], v[140:141], v[76:77]
	v_pk_add_f32 v[158:159], v[142:143], v[78:79]
	v_mul_f32_e32 v154, 0xbfb8aa3b, v154
	v_exp_f32_e32 v154, v154
	v_mul_f32_e32 v155, 0xbfb8aa3b, v155
	v_exp_f32_e32 v157, v155
	v_pk_add_f32 v[164:165], v[136:137], v[72:73]
	v_add_f32_e32 v154, 1.0, v154
	v_rcp_f32_e32 v155, v154
	v_add_f32_e32 v154, 1.0, v157
	v_mul_f32_e32 v157, 0xbfb8aa3b, v158
	v_exp_f32_e32 v158, v157
	v_mul_f32_e32 v157, 0xbfb8aa3b, v159
	v_exp_f32_e32 v159, v157
	v_rcp_f32_e32 v157, v154
	v_add_f32_e32 v154, 1.0, v158
	v_rcp_f32_e32 v158, v154
	v_add_f32_e32 v154, 1.0, v159
	v_rcp_f32_e32 v159, v154
	v_mul_f32_e32 v154, 0xbfb8aa3b, v164
	v_exp_f32_e32 v154, v154
	v_mul_f32_e32 v164, 0xbfb8aa3b, v165
	v_exp_f32_e32 v165, v164
	v_pk_add_f32 v[166:167], v[138:139], v[74:75]
	v_add_f32_e32 v154, 1.0, v154
	v_rcp_f32_e32 v164, v154
	v_add_f32_e32 v154, 1.0, v165
	v_mul_f32_e32 v165, 0xbfb8aa3b, v166
	v_exp_f32_e32 v166, v165
	v_mul_f32_e32 v165, 0xbfb8aa3b, v167
	v_exp_f32_e32 v167, v165
	v_rcp_f32_e32 v165, v154
	v_add_f32_e32 v154, 1.0, v166
	v_rcp_f32_e32 v166, v154
	v_add_f32_e32 v154, 1.0, v167
	v_rcp_f32_e32 v167, v154
